# split P0 + pipelined (16 KB in flight per wave) conversion of the LN-folded weights in the late pass
# speedup vs baseline: 1.0199x; 1.0053x over previous
.Lgv_begin:
	s_cmp_eq_u32 s99, 1
	s_cbranch_scc1 .Lgv_end
	s_mov_b32 s30, s0
	v_lshrrev_b32_e32 v2, 3, v244
	v_and_b32_e32 v3, 7, v244
	v_lshlrev_b32_e32 v5, 2, v244
	s_lshl_b32 s31, s85, 14
	v_lshlrev_b32_e32 v6, 7, v2
	v_add_u32_e32 v6, s31, v6
	v_xor_b32_e32 v8, 0, v3
	v_lshl_add_u32 v21, v8, 4, v6
	v_xor_b32_e32 v8, 1, v3
	v_lshl_add_u32 v22, v8, 4, v6
	v_xor_b32_e32 v8, 2, v3
	v_lshl_add_u32 v23, v8, 4, v6
	v_xor_b32_e32 v8, 3, v3
	v_lshl_add_u32 v24, v8, 4, v6
	v_xor_b32_e32 v8, 4, v3
	v_lshl_add_u32 v25, v8, 4, v6
	v_xor_b32_e32 v8, 5, v3
	v_lshl_add_u32 v26, v8, 4, v6
	v_xor_b32_e32 v8, 6, v3
	v_lshl_add_u32 v27, v8, 4, v6
	v_xor_b32_e32 v8, 7, v3
	v_lshl_add_u32 v28, v8, 4, v6
	v_lshlrev_b32_e32 v7, 10, v3
	v_add_u32_e32 v7, s31, v7
	v_add_u32_e32 v8, 0, v2
	v_lshrrev_b32_e32 v9, 2, v8
	v_xor_b32_e32 v9, v9, v3
	v_and_b32_e32 v8, 3, v8
	v_lshl_add_u32 v8, v9, 2, v8
	v_lshl_add_u32 v29, v8, 2, v7
	v_add_u32_e32 v8, 8, v2
	v_lshrrev_b32_e32 v9, 2, v8
	v_xor_b32_e32 v9, v9, v3
	v_and_b32_e32 v8, 3, v8
	v_lshl_add_u32 v8, v9, 2, v8
	v_lshl_add_u32 v30, v8, 2, v7
	v_add_u32_e32 v8, 16, v2
	v_lshrrev_b32_e32 v9, 2, v8
	v_xor_b32_e32 v9, v9, v3
	v_and_b32_e32 v8, 3, v8
	v_lshl_add_u32 v8, v9, 2, v8
	v_lshl_add_u32 v31, v8, 2, v7
	v_add_u32_e32 v8, 24, v2
	v_lshrrev_b32_e32 v9, 2, v8
	v_xor_b32_e32 v9, v9, v3
	v_and_b32_e32 v8, 3, v8
	v_lshl_add_u32 v8, v9, 2, v8
	v_lshl_add_u32 v32, v8, 2, v7
	v_lshl_add_u32 v8, v3, 3, v2
	v_lshlrev_b32_e32 v8, 2, v8
	v_add_u32_e32 v10, s31, v8
	v_add_u32_e32 v10, 0x2000, v10
	v_lshlrev_b32_e32 v8, 5, v2
	v_add_u32_e32 v11, s31, v8
	v_add_u32_e32 v11, 0x2000, v11
	v_xor_b32_e32 v8, 8, v244
	v_lshlrev_b32_e32 v12, 2, v8
	v_xor_b32_e32 v8, 16, v244
	v_lshlrev_b32_e32 v13, 2, v8
	v_xor_b32_e32 v8, 32, v244
	v_lshlrev_b32_e32 v14, 2, v8
	v_lshlrev_b32_e32 v15, 2, v2
	v_lshlrev_b32_e32 v16, 4, v3
	v_lshlrev_b32_e32 v17, 12, v2
	v_lshl_add_u32 v17, v3, 4, v17
	v_add_u32_e32 v18, 0x8000, v17
	v_add_u32_e32 v19, 0x10000, v17
	v_add_u32_e32 v20, 0x18000, v17
	s_mov_b32 s56, 0x1010101
	s_mov_b32 s57, 0x1010101
	s_mov_b64 s[64:65], 0xff
	s_mov_b32 s59, 0xffff0000
	s_waitcnt lgkmcnt(0)
	s_cmp_lt_u32 s30, 0x4000
	s_cbranch_scc1 .Lgv1_w1
	s_cmp_lt_u32 s30, 0x5000
	s_cbranch_scc1 .Lgv1_pg
	s_cmp_lt_u32 s30, 0x5800
	s_cbranch_scc1 .Lgv1_wq
	s_cmp_lt_u32 s30, 0x5a00
	s_cbranch_scc1 .Lgv1_wk
	s_cmp_lt_u32 s30, 0x5c00
	s_cbranch_scc1 .Lgv1_wv
	s_mov_b32 s12, 0
	s_load_dwordx2 s[4:5], s[18:19], 0x98
	s_load_dwordx2 s[6:7], s[18:19], 0x100
	s_load_dwordx2 s[8:9], s[18:19], 0x108
	s_mov_b32 s10, 11
	s_mov_b32 s11, 4
	s_mov_b32 s69, 0x2d200000
	s_mov_b32 s70, 0x2e200000
	s_mov_b32 s40, 0x3000
	s_mov_b32 s71, 0
	s_mov_b32 s72, 0
	s_branch .Lgv1_common

.Lgv5_common:
	s_lshr_b32 s13, s12, s11
	s_lshl_b32 s15, s13, s11
	s_sub_i32 s14, s12, s15
	s_add_i32 s15, s10, 6
	s_lshl_b32 s15, s13, s15
	s_lshl_b32 s21, s14, 7
	s_add_i32 s15, s15, s21
	s_lshl_b32 s29, 8, s10
	v_lshlrev_b32_e32 v4, s10, v2
	v_lshl_add_u32 v4, v3, 4, v4
	s_lshl_b32 s21, s13, 8
	s_waitcnt lgkmcnt(0)
	s_add_u32 s4, s4, s71
	s_addc_u32 s5, s5, 0
	s_add_u32 s4, s4, s15
	s_addc_u32 s5, s5, 0
	s_add_u32 s6, s6, s72
	s_addc_u32 s7, s7, 0
	s_add_u32 s6, s6, s21
	s_addc_u32 s7, s7, 0
	s_add_u32 s8, s8, s72
	s_addc_u32 s9, s9, 0
	s_add_u32 s8, s8, s21
	s_addc_u32 s9, s9, 0
	global_load_dwordx4 v[100:103], v4, s[4:5] nt
	s_add_u32 s4, s4, s29
	s_addc_u32 s5, s5, 0
	global_load_dwordx4 v[104:107], v4, s[4:5] nt
	s_add_u32 s4, s4, s29
	s_addc_u32 s5, s5, 0
	global_load_dwordx4 v[108:111], v4, s[4:5] nt
	s_add_u32 s4, s4, s29
	s_addc_u32 s5, s5, 0
	global_load_dwordx4 v[112:115], v4, s[4:5] nt
	s_add_u32 s4, s4, s29
	s_addc_u32 s5, s5, 0
	global_load_dwordx4 v[116:119], v4, s[4:5] nt
	s_add_u32 s4, s4, s29
	s_addc_u32 s5, s5, 0
	global_load_dwordx4 v[120:123], v4, s[4:5] nt
	s_add_u32 s4, s4, s29
	s_addc_u32 s5, s5, 0
	global_load_dwordx4 v[124:127], v4, s[4:5] nt
	s_add_u32 s4, s4, s29
	s_addc_u32 s5, s5, 0
	global_load_dwordx4 v[128:131], v4, s[4:5] nt
	global_load_dword v206, v5, s[6:7]
	global_load_dword v207, v5, s[8:9]
	s_lshl_b32 s15, s14, 17
	s_lshl_b32 s21, s13, 7
	s_add_i32 s15, s15, s21
	s_add_u32 s36, s16, s69
	s_addc_u32 s37, s17, 0
	s_add_u32 s36, s36, s15
	s_addc_u32 s37, s37, 0
	s_lshl_b32 s15, s14, 7
	s_add_u32 s38, s16, s70
	s_addc_u32 s39, s17, 0
	s_add_u32 s38, s38, s15
	s_addc_u32 s39, s39, 0
	s_addk_i32 s30, 0x800
	s_add_i32 s3, s3, -1
	s_cmp_lg_u32 s3, 0
	s_cbranch_scc1 .Lgv_loop
	s_waitcnt vmcnt(22)
	ds_write_b32 v10, v208
	ds_write_b32 v10, v209 offset:256
	ds_read_b128 v[210:213], v11
	ds_read_b128 v[214:217], v11 offset:16
	ds_read_b128 v[218:221], v11 offset:256
	ds_read_b128 v[222:225], v11 offset:272
	s_waitcnt lgkmcnt(0)
	v_mul_f32_e32 v226, v132, v218
	v_mul_f32_e32 v132, v132, v210
	v_mul_f32_e32 v227, v133, v218
	v_mul_f32_e32 v133, v133, v210
	v_mul_f32_e32 v228, v134, v218
	v_mul_f32_e32 v134, v134, v210
	v_mul_f32_e32 v229, v135, v218
	v_mul_f32_e32 v135, v135, v210
	v_fmac_f32_e32 v226, v136, v219
	v_mul_f32_e32 v136, v136, v211
	v_fmac_f32_e32 v227, v137, v219
	v_mul_f32_e32 v137, v137, v211
	v_fmac_f32_e32 v228, v138, v219
	v_mul_f32_e32 v138, v138, v211
	v_fmac_f32_e32 v229, v139, v219
	v_mul_f32_e32 v139, v139, v211
	v_fmac_f32_e32 v226, v140, v220
	v_mul_f32_e32 v140, v140, v212
	v_fmac_f32_e32 v227, v141, v220
	v_mul_f32_e32 v141, v141, v212
	v_fmac_f32_e32 v228, v142, v220
	v_mul_f32_e32 v142, v142, v212
	v_fmac_f32_e32 v229, v143, v220
	v_mul_f32_e32 v143, v143, v212
	v_fmac_f32_e32 v226, v144, v221
	v_mul_f32_e32 v144, v144, v213
	v_fmac_f32_e32 v227, v145, v221
	v_mul_f32_e32 v145, v145, v213
	v_fmac_f32_e32 v228, v146, v221
	v_mul_f32_e32 v146, v146, v213
	v_fmac_f32_e32 v229, v147, v221
	v_mul_f32_e32 v147, v147, v213
	v_fmac_f32_e32 v226, v148, v222
	v_mul_f32_e32 v148, v148, v214
	v_fmac_f32_e32 v227, v149, v222
	v_mul_f32_e32 v149, v149, v214
	v_fmac_f32_e32 v228, v150, v222
	v_mul_f32_e32 v150, v150, v214
	v_fmac_f32_e32 v229, v151, v222
	v_mul_f32_e32 v151, v151, v214
	v_fmac_f32_e32 v226, v152, v223
	v_mul_f32_e32 v152, v152, v215
	v_fmac_f32_e32 v227, v153, v223
	v_mul_f32_e32 v153, v153, v215
	v_fmac_f32_e32 v228, v154, v223
	v_mul_f32_e32 v154, v154, v215
	v_fmac_f32_e32 v229, v155, v223
	v_mul_f32_e32 v155, v155, v215
	v_fmac_f32_e32 v226, v156, v224
	v_mul_f32_e32 v156, v156, v216
	v_fmac_f32_e32 v227, v157, v224
	v_mul_f32_e32 v157, v157, v216
	v_fmac_f32_e32 v228, v158, v224
	v_mul_f32_e32 v158, v158, v216
	v_fmac_f32_e32 v229, v159, v224
	v_mul_f32_e32 v159, v159, v216
	v_fmac_f32_e32 v226, v160, v225
	v_mul_f32_e32 v160, v160, v217
	v_fmac_f32_e32 v227, v161, v225
	v_mul_f32_e32 v161, v161, v217
	v_fmac_f32_e32 v228, v162, v225
	v_mul_f32_e32 v162, v162, v217
	v_fmac_f32_e32 v229, v163, v225
	v_mul_f32_e32 v163, v163, v217
	ds_write_b128 v21, v[132:135]
	ds_write_b128 v22, v[136:139] offset:1024
	ds_write_b128 v23, v[140:143] offset:2048
	ds_write_b128 v24, v[144:147] offset:3072
	ds_write_b128 v25, v[148:151] offset:4096
	ds_write_b128 v26, v[152:155] offset:5120
	ds_write_b128 v27, v[156:159] offset:6144
	ds_write_b128 v28, v[160:163] offset:7168
	ds_read2_b32 v[132:133], v29 offset1:32
	ds_read2_b32 v[134:135], v29 offset0:64 offset1:96
	ds_read2_b32 v[136:137], v29 offset0:128 offset1:160
	ds_read2_b32 v[138:139], v29 offset0:192 offset1:224
	ds_read2_b32 v[140:141], v30 offset1:32
	ds_read2_b32 v[142:143], v30 offset0:64 offset1:96
	ds_read2_b32 v[144:145], v30 offset0:128 offset1:160
	ds_read2_b32 v[146:147], v30 offset0:192 offset1:224
	ds_read2_b32 v[148:149], v31 offset1:32
	ds_read2_b32 v[150:151], v31 offset0:64 offset1:96
	ds_read2_b32 v[152:153], v31 offset0:128 offset1:160
	ds_read2_b32 v[154:155], v31 offset0:192 offset1:224
	ds_read2_b32 v[156:157], v32 offset1:32
	ds_read2_b32 v[158:159], v32 offset0:64 offset1:96
	ds_read2_b32 v[160:161], v32 offset0:128 offset1:160
	ds_read2_b32 v[162:163], v32 offset0:192 offset1:224
	ds_bpermute_b32 v234, v12, v226
	ds_bpermute_b32 v235, v12, v227
	ds_bpermute_b32 v236, v12, v228
	ds_bpermute_b32 v237, v12, v229
	s_waitcnt lgkmcnt(4)
	v_cvt_pk_bf16_f32 v190, v132, v133
	v_cvt_pk_bf16_f32 v191, v134, v135
	v_cvt_pk_bf16_f32 v192, v136, v137
	v_cvt_pk_bf16_f32 v193, v138, v139
	v_cvt_pk_bf16_f32 v194, v140, v141
	v_cvt_pk_bf16_f32 v195, v142, v143
	v_cvt_pk_bf16_f32 v196, v144, v145
	v_cvt_pk_bf16_f32 v197, v146, v147
	v_cvt_pk_bf16_f32 v198, v148, v149
	v_cvt_pk_bf16_f32 v199, v150, v151
	v_cvt_pk_bf16_f32 v200, v152, v153
	v_cvt_pk_bf16_f32 v201, v154, v155
	v_cvt_pk_bf16_f32 v202, v156, v157
	v_cvt_pk_bf16_f32 v203, v158, v159
	v_cvt_pk_bf16_f32 v204, v160, v161
	v_cvt_pk_bf16_f32 v205, v162, v163
	s_waitcnt lgkmcnt(0)
	v_add_f32_e32 v226, v226, v234
	v_add_f32_e32 v227, v227, v235
	v_add_f32_e32 v228, v228, v236
	v_add_f32_e32 v229, v229, v237
	ds_bpermute_b32 v234, v13, v226
	ds_bpermute_b32 v235, v13, v227
	ds_bpermute_b32 v236, v13, v228
	ds_bpermute_b32 v237, v13, v229
	v_lshlrev_b32_e32 v238, 16, v190
	v_and_b32_e32 v239, s59, v190
	v_add_f32_e32 v230, v238, v239
	v_lshlrev_b32_e32 v238, 16, v191
	v_and_b32_e32 v239, s59, v191
	v_add_f32_e32 v230, v230, v238
	v_add_f32_e32 v230, v230, v239
	v_lshlrev_b32_e32 v238, 16, v192
	v_and_b32_e32 v239, s59, v192
	v_add_f32_e32 v230, v230, v238
	v_add_f32_e32 v230, v230, v239
	v_lshlrev_b32_e32 v238, 16, v193
	v_and_b32_e32 v239, s59, v193
	v_add_f32_e32 v230, v230, v238
	v_add_f32_e32 v230, v230, v239
	v_lshlrev_b32_e32 v238, 16, v194
	v_and_b32_e32 v239, s59, v194
	v_add_f32_e32 v231, v238, v239
	v_lshlrev_b32_e32 v238, 16, v195
	v_and_b32_e32 v239, s59, v195
	v_add_f32_e32 v231, v231, v238
	v_add_f32_e32 v231, v231, v239
	v_lshlrev_b32_e32 v238, 16, v196
	v_and_b32_e32 v239, s59, v196
	v_add_f32_e32 v231, v231, v238
	v_add_f32_e32 v231, v231, v239
	v_lshlrev_b32_e32 v238, 16, v197
	v_and_b32_e32 v239, s59, v197
	v_add_f32_e32 v231, v231, v238
	v_add_f32_e32 v231, v231, v239
	s_waitcnt lgkmcnt(0)
	v_add_f32_e32 v226, v226, v234
	v_add_f32_e32 v227, v227, v235
	v_add_f32_e32 v228, v228, v236
	v_add_f32_e32 v229, v229, v237
	ds_bpermute_b32 v234, v14, v226
	ds_bpermute_b32 v235, v14, v227
	ds_bpermute_b32 v236, v14, v228
	ds_bpermute_b32 v237, v14, v229
	v_lshlrev_b32_e32 v238, 16, v198
	v_and_b32_e32 v239, s59, v198
	v_add_f32_e32 v232, v238, v239
	v_lshlrev_b32_e32 v238, 16, v199
	v_and_b32_e32 v239, s59, v199
	v_add_f32_e32 v232, v232, v238
	v_add_f32_e32 v232, v232, v239
	v_lshlrev_b32_e32 v238, 16, v200
	v_and_b32_e32 v239, s59, v200
	v_add_f32_e32 v232, v232, v238
	v_add_f32_e32 v232, v232, v239
	v_lshlrev_b32_e32 v238, 16, v201
	v_and_b32_e32 v239, s59, v201
	v_add_f32_e32 v232, v232, v238
	v_add_f32_e32 v232, v232, v239
	v_lshlrev_b32_e32 v238, 16, v202
	v_and_b32_e32 v239, s59, v202
	v_add_f32_e32 v233, v238, v239
	v_lshlrev_b32_e32 v238, 16, v203
	v_and_b32_e32 v239, s59, v203
	v_add_f32_e32 v233, v233, v238
	v_add_f32_e32 v233, v233, v239
	v_lshlrev_b32_e32 v238, 16, v204
	v_and_b32_e32 v239, s59, v204
	v_add_f32_e32 v233, v233, v238
	v_add_f32_e32 v233, v233, v239
	v_lshlrev_b32_e32 v238, 16, v205
	v_and_b32_e32 v239, s59, v205
	v_add_f32_e32 v233, v233, v238
	v_add_f32_e32 v233, v233, v239
	s_nop 1
	v_add_f32_dpp v230, v230, v230 quad_perm:[1,0,3,2] row_mask:0xf bank_mask:0xf
	v_add_f32_dpp v231, v231, v231 quad_perm:[1,0,3,2] row_mask:0xf bank_mask:0xf
	v_add_f32_dpp v232, v232, v232 quad_perm:[1,0,3,2] row_mask:0xf bank_mask:0xf
	v_add_f32_dpp v233, v233, v233 quad_perm:[1,0,3,2] row_mask:0xf bank_mask:0xf
	v_add_f32_dpp v230, v230, v230 quad_perm:[2,3,0,1] row_mask:0xf bank_mask:0xf
	v_add_f32_dpp v231, v231, v231 quad_perm:[2,3,0,1] row_mask:0xf bank_mask:0xf
	v_add_f32_dpp v232, v232, v232 quad_perm:[2,3,0,1] row_mask:0xf bank_mask:0xf
	v_add_f32_dpp v233, v233, v233 quad_perm:[2,3,0,1] row_mask:0xf bank_mask:0xf
	v_add_f32_dpp v230, v230, v230 row_half_mirror row_mask:0xf bank_mask:0xf
	v_add_f32_dpp v231, v231, v231 row_half_mirror row_mask:0xf bank_mask:0xf
	v_add_f32_dpp v232, v232, v232 row_half_mirror row_mask:0xf bank_mask:0xf
	v_add_f32_dpp v233, v233, v233 row_half_mirror row_mask:0xf bank_mask:0xf
	s_waitcnt lgkmcnt(0)
	v_add_f32_e32 v226, v226, v234
	v_add_f32_e32 v227, v227, v235
	v_add_f32_e32 v228, v228, v236
	v_add_f32_e32 v229, v229, v237
	global_store_dwordx4 v17, v[190:193], s[42:43]
	global_store_dwordx4 v18, v[194:197], s[42:43]
	global_store_dwordx4 v19, v[198:201], s[42:43]
	global_store_dwordx4 v20, v[202:205], s[42:43]
	s_add_u32 s48, s44, s47
	s_addc_u32 s49, s45, 0
	s_mov_b64 exec, s[56:57]
	global_atomic_add_f32 v15, v230, s[44:45]
	global_atomic_add_f32 v15, v231, s[44:45] offset:32
	global_atomic_add_f32 v15, v232, s[44:45] offset:64
	global_atomic_add_f32 v15, v233, s[44:45] offset:96
	s_mov_b64 exec, s[64:65]
	global_atomic_add_f32 v16, v226, s[48:49]
	global_atomic_add_f32 v16, v227, s[48:49] offset:4
	global_atomic_add_f32 v16, v228, s[48:49] offset:8
	global_atomic_add_f32 v16, v229, s[48:49] offset:12
	s_mov_b64 exec, -1
	s_waitcnt vmcnt(0) lgkmcnt(0)
.Lgv_end:
	s_lshl_b32 s8, s85, 14
	v_and_b32_e32 v1, 7, v0
	v_lshrrev_b32_e32 v7, 3, v244
	s_add_i32 s3, s8, 0
	v_mul_u32_u24_e32 v4, 0x420, v1
	v_lshlrev_b32_e32 v9, 2, v7
	v_and_b32_e32 v32, 31, v0
	v_mov_b32_e32 v5, 0
	v_add3_u32 v9, s3, v4, v9
	v_lshlrev_b32_e32 v4, 4, v1
	v_lshlrev_b32_e32 v34, 2, v32
	s_waitcnt lgkmcnt(0)
	v_lshl_add_u64 v[28:29], s[16:17], 0, v[4:5]
	s_mov_b64 s[6:7], 0x6700000
	v_mov_b32_e32 v35, v5
	v_lshl_add_u64 v[10:11], v[28:29], 0, s[6:7]
	v_lshl_add_u64 v[24:25], s[16:17], 0, v[34:35]
	s_mov_b64 s[6:7], 0x195000
	v_lshl_add_u64 v[12:13], v[24:25], 0, s[6:7]
	s_mov_b64 s[6:7], 0x198000
	v_lshl_add_u64 v[14:15], v[24:25], 0, s[6:7]
	s_mov_b64 s[6:7], 0x5b00000
	v_lshl_add_u64 v[16:17], v[28:29], 0, s[6:7]
	s_mov_b64 s[6:7], 0x194800
	v_lshl_add_u64 v[18:19], v[24:25], 0, s[6:7]
	s_mov_b64 s[6:7], 0x197800
	v_lshl_add_u64 v[20:21], v[24:25], 0, s[6:7]
	s_mov_b64 s[6:7], 0x194000
	v_lshl_add_u64 v[22:23], v[24:25], 0, s[6:7]
	s_mov_b64 s[6:7], 0x197000
	v_lshl_add_u64 v[24:25], v[24:25], 0, s[6:7]
	s_mov_b64 s[6:7], 0xa00000
	v_bfe_u32 v4, v0, 5, 1
	v_lshl_add_u64 v[26:27], v[28:29], 0, s[6:7]
	s_mov_b64 s[6:7], 0x200000
	v_lshlrev_b32_e32 v30, 7, v4
	v_mul_u32_u24_e32 v4, 0x1080, v4
	s_add_u32 s0, s16, 0x180000
	v_lshl_add_u64 v[28:29], v[28:29], 0, s[6:7]
	v_readlane_b32 s6, v255, 8
	v_or3_b32 v4, s8, v4, v34
	s_addc_u32 s1, s17, 0
	v_lshrrev_b32_e32 v2, 5, v244
	v_add_u32_e32 v6, s3, v34
	s_mov_b32 s10, s6
	s_add_i32 s3, s6, 0x9b00
	v_add_u32_e32 v47, 0, v4
	s_add_i32 s30, s6, 0xec00
	s_lshl_b32 s6, s6, 2
	v_mbcnt_lo_u32_b32 v4, -1, 0
	s_mov_b32 s21, 0
	v_and_b32_e32 v3, 32, v0
	v_cmp_gt_u32_e64 s[4:5], 32, v244
	v_lshlrev_b32_e32 v8, 3, v1
	v_or_b32_e32 v44, 8, v7
	v_or_b32_e32 v45, 16, v7
	v_or_b32_e32 v46, 24, v7
	v_mov_b32_e32 v1, v2
	v_mov_b32_e32 v31, v5
	s_add_i32 s31, s6, 0x3b800
	s_lshl_b32 s33, s94, 5
	s_add_i32 s36, s6, 0x3c000
	s_movk_i32 s37, 0x84
	s_movk_i32 s38, 0x7fff
	s_mov_b32 s39, 0xffff0000
	s_mov_b32 s40, 0x10000
	s_mov_b32 s41, 0x5300000
	s_mov_b32 s42, 0x5200000
	s_mov_b32 s43, 0x3200000
	s_mov_b32 s44, 0x1200000
	v_lshlrev_b32_e32 v32, 2, v32
	v_mbcnt_hi_u32_b32 v48, -1, v4
	s_mov_b32 s45, s10
	v_readlane_b32 s7, v255, 9
	s_branch .LBB0_19

.LBB0_19:
	s_cmpk_lt_u32 s45, 0x800
	s_cselect_b32 s98, 1, 0
	s_sub_u32 s100, s45, 0x6400
	s_cmpk_lt_u32 s100, 0x100
	s_cselect_b32 s98, 1, s98
	s_sub_u32 s100, s45, 0xad00
	s_cmpk_lt_u32 s100, 0x100
	s_cselect_b32 s98, 1, s98
	s_cmp_lg_u32 s98, s99
	s_cbranch_scc1 .LBB0_18
	s_cmpk_gt_i32 s45, 0x7ff
	s_mov_b64 s[6:7], -1
	s_cbranch_scc0 .LBB0_181
	s_cmpk_gt_u32 s45, 0xfff
	s_cbranch_scc0 .LBB0_176
	s_waitcnt lgkmcnt(0)
	s_load_dwordx4 s[8:11], s[18:19], 0x100
	s_cmpk_gt_u32 s45, 0x11ff
	s_cbranch_scc0 .LBB0_149
	s_cmpk_gt_u32 s45, 0x13ff
	s_cbranch_scc0 .LBB0_122
	s_cmpk_gt_u32 s45, 0x1bff
	s_cbranch_scc0 .LBB0_95
	s_add_i32 s46, s45, 0xffffe400
	s_cmpk_gt_u32 s46, 0x7ff
	s_cbranch_scc0 .LBB0_90
	s_add_i32 s28, s45, 0xffffdc00
	s_cmpk_gt_u32 s28, 0x48ff
	s_cselect_b64 s[22:23], -1, 0
	s_and_b64 s[6:7], s[22:23], exec
	s_cselect_b32 s20, 0xffffb700, 0
	s_add_i32 s29, s20, s28
	s_cmpk_gt_i32 s29, 0x1fff
	s_mov_b64 s[6:7], -1
	s_cbranch_scc0 .LBB0_63
	s_cmpk_gt_u32 s29, 0x3fff
	s_cbranch_scc0 .LBB0_58
	s_cmpk_gt_u32 s29, 0x40ff
	s_cbranch_scc0 .LBB0_53
	s_mov_b64 s[6:7], 0
	s_branch .LBB0_53
	s_load_dwordx4 s[12:15], s[18:19], 0xe0
	s_load_dwordx2 s[24:25], s[18:19], 0xf8
	s_and_b64 s[26:27], s[22:23], exec
	s_cselect_b32 s49, 0x800, 0
	s_lshl_b32 s7, s49, 13
	v_mov_b32_e32 v33, v5
	s_waitcnt lgkmcnt(0)
	s_add_u32 s7, s24, s7
	s_addc_u32 s25, s25, 0
	s_add_i32 s24, s29, 0xbf00
	s_and_b32 s48, s24, 0xffc0
	s_lshl_b32 s24, s45, 5
	s_and_b32 s47, s24, 0x7e0
	s_lshl_b32 s24, s47, 2
	s_add_u32 s24, s7, s24
	s_addc_u32 s25, s25, 0
	s_mov_b32 s6, 0
	v_lshl_add_u64 v[34:35], s[24:25], 0, v[32:33]
	s_mov_b32 s7, s48
	s_mov_b32 s24, 1
	s_mov_b32 s25, 32
